# P7 prompt attention: all waves lag + fused fast path (QK then softmax VALU interleaved with pending PV MFMAs, pipelined LDS reads)
# speedup vs baseline: 1.0134x; 1.0134x over previous
.LBB0_455:
	v_lshrrev_b32_e32 v0, 2, v3
	v_lshlrev_b32_e32 v7, 10, v4
	v_lshlrev_b32_e32 v8, 8, v0
	v_and_b32_e32 v6, 32, v6
	v_lshlrev_b32_e32 v5, 3, v5
	v_or3_b32 v6, v7, v8, v6
	v_and_b32_e32 v5, 24, v5
	v_lshlrev_b32_e32 v0, 6, v0
	v_or3_b32 v0, v6, v5, v0
	s_movk_i32 s0, 0x80
	v_bitop3_b32 v229, v0, s0, v217 bitop3:0x36
	s_movk_i32 s0, 0xc0
	s_cmp_gt_i32 s20, 3
	v_lshlrev_b32_e32 v202, 2, v4
	v_or_b32_e32 v227, 0x4000, v0
	v_bitop3_b32 v228, v0, 64, v217 bitop3:0x36
	v_bitop3_b32 v230, v0, s0, v217 bitop3:0x36
	s_mov_b64 s[84:85], -1
	s_cmp_lt_i32 s25, 1
	s_mov_b32 s27, 0
	s_cbranch_scc1 .LBB0_498
	s_not_b32 s1, s23
	s_lshl_b32 s1, s1, 1
	v_ldexp_f32 v0, 1.0, s1
	v_or_b32_e32 v198, s24, v226
	v_mul_f32_e32 v196, 0x3fb8aa3b, v0
	v_sub_u32_e32 v0, v202, v198
	v_add_u32_e32 v5, 1, v0
	v_cvt_f32_i32_e32 v6, v0
	v_cvt_f32_i32_e32 v7, v5
	v_add_u32_e32 v5, 2, v0
	v_add_u32_e32 v8, 3, v0
	v_cvt_f32_i32_e32 v9, v8
	v_cvt_f32_i32_e32 v8, v5
	v_add_u32_e32 v5, 8, v0
	v_add_u32_e32 v10, 9, v0
	v_cvt_f32_i32_e32 v11, v10
	v_cvt_f32_i32_e32 v10, v5
	v_mov_b32_e32 v197, v196
	v_add_u32_e32 v5, 10, v0
	v_add_u32_e32 v12, 11, v0
	v_cvt_f32_i32_e32 v13, v12
	v_cvt_f32_i32_e32 v12, v5
	v_pk_mul_f32 v[80:81], v[196:197], v[6:7] op_sel_hi:[0,1]
	v_add_u32_e32 v5, 16, v0
	v_add_u32_e32 v6, 17, v0
	v_pk_mul_f32 v[82:83], v[196:197], v[8:9] op_sel_hi:[0,1]
	v_cvt_f32_i32_e32 v7, v6
	v_cvt_f32_i32_e32 v6, v5
	v_add_u32_e32 v5, 18, v0
	v_add_u32_e32 v8, 19, v0
	v_pk_mul_f32 v[84:85], v[196:197], v[10:11] op_sel_hi:[0,1]
	v_cvt_f32_i32_e32 v9, v8
	v_cvt_f32_i32_e32 v8, v5
	v_add_u32_e32 v5, 24, v0
	v_add_u32_e32 v10, 25, v0
	v_cvt_f32_i32_e32 v11, v10
	v_cvt_f32_i32_e32 v10, v5
	v_pk_mul_f32 v[86:87], v[196:197], v[12:13] op_sel_hi:[0,1]
	v_add_u32_e32 v5, 26, v0
	v_add_u32_e32 v12, 27, v0
	v_cvt_f32_i32_e32 v13, v12
	v_cvt_f32_i32_e32 v12, v5
	v_pk_mul_f32 v[88:89], v[196:197], v[6:7] op_sel_hi:[0,1]
	v_add_u32_e32 v5, 32, v0
	v_add_u32_e32 v6, 33, v0
	v_pk_mul_f32 v[90:91], v[196:197], v[8:9] op_sel_hi:[0,1]
	v_cvt_f32_i32_e32 v7, v6
	v_cvt_f32_i32_e32 v6, v5
	v_add_u32_e32 v5, 34, v0
	v_add_u32_e32 v8, 35, v0
	v_pk_mul_f32 v[92:93], v[196:197], v[10:11] op_sel_hi:[0,1]
	v_cvt_f32_i32_e32 v9, v8
	v_cvt_f32_i32_e32 v8, v5
	v_add_u32_e32 v5, 40, v0
	v_add_u32_e32 v10, 41, v0
	v_cvt_f32_i32_e32 v11, v10
	v_cvt_f32_i32_e32 v10, v5
	v_pk_mul_f32 v[94:95], v[196:197], v[12:13] op_sel_hi:[0,1]
	v_add_u32_e32 v5, 42, v0
	v_add_u32_e32 v12, 43, v0
	v_cvt_f32_i32_e32 v13, v12
	v_cvt_f32_i32_e32 v12, v5
	v_pk_mul_f32 v[96:97], v[196:197], v[6:7] op_sel_hi:[0,1]
	v_add_u32_e32 v5, 48, v0
	v_add_u32_e32 v6, 49, v0
	s_lshl_b32 s0, s20, 2
	v_pk_mul_f32 v[98:99], v[196:197], v[8:9] op_sel_hi:[0,1]
	v_cvt_f32_i32_e32 v7, v6
	v_cvt_f32_i32_e32 v6, v5
	v_add_u32_e32 v5, 50, v0
	v_add_u32_e32 v8, 51, v0
	s_add_i32 s28, s0, 0
	s_lshl_b32 s0, s96, 1
	s_lshr_b32 s1, s22, 1
	v_pk_mul_f32 v[100:101], v[196:197], v[10:11] op_sel_hi:[0,1]
	v_cvt_f32_i32_e32 v9, v8
	v_cvt_f32_i32_e32 v8, v5
	v_add_u32_e32 v5, 56, v0
	v_add_u32_e32 v10, 57, v0
	s_or_b32 s37, s1, s0
	v_cvt_f32_i32_e32 v11, v10
	v_cvt_f32_i32_e32 v10, v5
	v_add_u32_e32 v5, 58, v0
	v_add_u32_e32 v0, 59, v0
	s_lshl_b32 s0, s46, 3
	v_pk_mul_f32 v[102:103], v[196:197], v[12:13] op_sel_hi:[0,1]
	v_cvt_f32_i32_e32 v13, v0
	v_cvt_f32_i32_e32 v12, v5
	v_lshlrev_b32_e32 v0, 8, v2
	v_or_b32_e32 v5, s0, v4
	v_bitop3_b32 v4, s0, v3, v4 bitop3:0x36
	v_lshl_add_u32 v233, v4, 4, v0
	v_bitop3_b32 v4, v5, v3, 2 bitop3:0x36
	v_lshl_add_u32 v234, v4, 4, v0
	v_bitop3_b32 v4, v5, v3, 4 bitop3:0x36
	v_bitop3_b32 v3, v5, v3, 6 bitop3:0x36
	s_addk_i32 s30, 0x1fc1
	v_lshl_add_u32 v235, v4, 4, v0
	v_lshl_add_u32 v236, v3, 4, v0
	s_lshl_b32 s31, s25, 6
	v_add_u32_e32 v0, s30, v2
	v_subrev_u32_e32 v0, s31, v0
	s_lshl_b32 s19, s19, 7
	v_mov_b32_e32 v14, v1
	v_mov_b32_e32 v15, v1
	v_mov_b32_e32 v172, v1
	v_mov_b32_e32 v173, v1
	s_add_i32 s29, s24, 0x80
	v_pk_mul_f32 v[104:105], v[196:197], v[6:7] op_sel_hi:[0,1]
	v_pk_mul_f32 v[106:107], v[196:197], v[8:9] op_sel_hi:[0,1]
	v_pk_mul_f32 v[108:109], v[196:197], v[10:11] op_sel_hi:[0,1]
	v_pk_mul_f32 v[110:111], v[196:197], v[12:13] op_sel_hi:[0,1]
	s_lshl_b32 s34, s25, 3
	v_subrev_u32_e32 v237, s19, v0
	s_lshl_b32 s19, s25, 5
	v_mov_b32_e32 v0, v1
	v_mov_b32_e32 v2, v1
	v_mov_b32_e32 v3, v1
	v_mov_b32_e32 v4, v1
	v_mov_b32_e32 v5, v1
	v_mov_b32_e32 v6, v1
	v_mov_b32_e32 v7, v1
	v_mov_b32_e32 v8, v1
	v_mov_b32_e32 v9, v1
	v_mov_b32_e32 v10, v1
	v_mov_b32_e32 v11, v1
	v_mov_b32_e32 v12, v1
	v_mov_b32_e32 v13, v1
	v_mov_b32_e32 v174, v1
	v_mov_b32_e32 v175, v1
	v_mov_b64_e32 v[168:169], v[172:173]
	v_mov_b64_e32 v[164:165], v[172:173]
	v_mov_b64_e32 v[160:161], v[172:173]
	v_mov_b64_e32 v[78:79], v[14:15]
	v_mov_b64_e32 v[62:63], v[14:15]
	v_mov_b64_e32 v[46:47], v[14:15]
	v_mov_b64_e32 v[30:31], v[14:15]
	s_xor_b64 s[88:89], s[82:83], -1
	s_add_i32 s28, s28, 0x20040
	v_cmp_eq_u32_e64 s[0:1], 0, v203
	s_mov_b32 s47, s29
	v_mov_b32_e32 v199, v198
	s_sub_i32 s67, s31, 64
	s_add_i32 s72, s34, -16
	s_sub_i32 s81, s19, 32
	s_mov_b64 s[96:97], 0
	v_mov_b32_e32 v201, 0xf149f2ca
	v_mov_b32_e32 v232, 0
	v_mov_b64_e32 v[170:171], v[174:175]
	v_mov_b64_e32 v[166:167], v[174:175]
	v_mov_b64_e32 v[162:163], v[174:175]
	v_mov_b64_e32 v[76:77], v[12:13]
	v_mov_b64_e32 v[74:75], v[10:11]
	v_mov_b64_e32 v[72:73], v[8:9]
	v_mov_b64_e32 v[70:71], v[6:7]
	v_mov_b64_e32 v[68:69], v[4:5]
	v_mov_b64_e32 v[66:67], v[2:3]
	v_mov_b64_e32 v[64:65], v[0:1]
	v_mov_b64_e32 v[60:61], v[12:13]
	v_mov_b64_e32 v[58:59], v[10:11]
	v_mov_b64_e32 v[56:57], v[8:9]
	v_mov_b64_e32 v[54:55], v[6:7]
	v_mov_b64_e32 v[52:53], v[4:5]
	v_mov_b64_e32 v[50:51], v[2:3]
	v_mov_b64_e32 v[48:49], v[0:1]
	v_mov_b64_e32 v[44:45], v[12:13]
	v_mov_b64_e32 v[42:43], v[10:11]
	v_mov_b64_e32 v[40:41], v[8:9]
	v_mov_b64_e32 v[38:39], v[6:7]
	v_mov_b64_e32 v[36:37], v[4:5]
	v_mov_b64_e32 v[34:35], v[2:3]
	v_mov_b64_e32 v[32:33], v[0:1]
	v_mov_b64_e32 v[28:29], v[12:13]
	v_mov_b64_e32 v[26:27], v[10:11]
	v_mov_b64_e32 v[24:25], v[8:9]
	v_mov_b64_e32 v[22:23], v[6:7]
	v_mov_b64_e32 v[20:21], v[4:5]
	v_mov_b64_e32 v[18:19], v[2:3]
	v_mov_b64_e32 v[16:17], v[0:1]
	s_mov_b32 s50, 0
	s_branch .LBB0_458

.LBB0_460:
	s_andn2_b64 vcc, exec, s[42:43]
	s_cbranch_vccnz .LBB0_457
	v_sub_u32_e64 v0, s80, 2 clamp
	v_lshlrev_b64 v[2:3], 16, v[0:1]
	s_lshl_b32 s30, s50, 15
	v_lshl_add_u64 v[4:5], s[48:49], 0, v[2:3]
	s_xor_b32 s19, s30, 0x10000
	v_lshl_add_u64 v[2:3], s[60:61], 0, v[2:3]
	s_add_i32 s19, s19, s26
	v_lshl_add_u64 v[6:7], v[4:5], 0, v[188:189]
	s_mov_b32 m0, s19
	s_nop 0
	global_load_lds_dwordx4 v[6:7], off
	s_add_i32 s31, s19, 0x4000
	v_lshl_add_u64 v[6:7], v[2:3], 0, v[190:191]
	s_mov_b32 m0, s31
	s_nop 0
	global_load_lds_dwordx4 v[6:7], off
	v_lshl_add_u64 v[4:5], v[4:5], 0, v[192:193]
	s_add_i32 s31, s19, 0x400
	s_mov_b32 m0, s31
	s_nop 0
	global_load_lds_dwordx4 v[4:5], off
	v_lshl_add_u64 v[2:3], v[2:3], 0, v[194:195]
	s_addk_i32 s19, 0x4400
	s_mov_b32 m0, s19
	s_nop 0
	global_load_lds_dwordx4 v[2:3], off
	s_and_b64 s[34:35], s[84:85], s[96:97]
	s_andn2_b64 vcc, exec, s[34:35]
	s_cbranch_vccnz .LBB0_463
	s_add_i32 s19, s25, -1
	s_cmp_gt_i32 s19, s37
	s_cbranch_scc1 .Lfa_slow
	s_add_i32 s19, s67, 63
	s_cmp_lt_i32 s19, s24
	s_cbranch_scc0 .Lfa_slow
	s_cmp_lt_i32 s67, s29
	s_cbranch_scc0 .Lfa_slow
.Lfa_body:
	s_add_i32 s25, s25, -1
	v_add_u32_e32 v0, s30, v233
	v_add_u32_e32 v14, s30, v234
	v_add_u32_e32 v15, s30, v235
	v_add_u32_e32 v238, s30, v236
	ds_read_b128 v[2:5], v0
	ds_read_b128 v[6:9], v0 offset:8192
	ds_read_b128 v[10:13], v14
	ds_read_b128 v[212:215], v14 offset:8192
	ds_read_b128 v[240:243], v15
	ds_read_b128 v[244:247], v15 offset:8192
	v_add_u32_e32 v248, s27, v227
	v_add_u32_e32 v249, s27, v228
	v_add_u32_e32 v250, s27, v229
	v_add_u32_e32 v251, s27, v230
	s_waitcnt lgkmcnt(4)
	v_mfma_f32_32x32x16_bf16 v[128:143], v[2:5], v[144:147], v[80:95]
	v_mfma_f32_32x32x16_bf16 v[112:127], v[6:9], v[144:147], v[96:111]
	ds_read_b128 v[2:5], v238
	ds_read_b128 v[6:9], v238 offset:8192
	s_waitcnt lgkmcnt(4)
	v_mfma_f32_32x32x16_bf16 v[128:143], v[10:13], v[148:151], v[128:143]
	v_mfma_f32_32x32x16_bf16 v[112:127], v[212:215], v[148:151], v[112:127]
	ds_read_b64_tr_b16 v[10:11], v248 offset:0
	ds_read_b64_tr_b16 v[12:13], v248 offset:2048
	ds_read_b64_tr_b16 v[212:213], v249 offset:0
	ds_read_b64_tr_b16 v[214:215], v249 offset:2048
	s_waitcnt lgkmcnt(6)
	v_mfma_f32_32x32x16_bf16 v[128:143], v[240:243], v[152:155], v[128:143]
	v_mfma_f32_32x32x16_bf16 v[112:127], v[244:247], v[152:155], v[112:127]
	ds_read_b64_tr_b16 v[240:241], v250 offset:0
	ds_read_b64_tr_b16 v[242:243], v250 offset:2048
	ds_read_b64_tr_b16 v[244:245], v251 offset:0
	ds_read_b64_tr_b16 v[246:247], v251 offset:2048
	s_waitcnt lgkmcnt(8)
	v_mfma_f32_32x32x16_bf16 v[128:143], v[2:5], v[156:159], v[128:143]
	v_mfma_f32_32x32x16_bf16 v[112:127], v[6:9], v[156:159], v[112:127]
	ds_read_b64_tr_b16 v[2:3], v248 offset:4096
	ds_read_b64_tr_b16 v[4:5], v248 offset:6144
	ds_read_b64_tr_b16 v[6:7], v249 offset:4096
	ds_read_b64_tr_b16 v[8:9], v249 offset:6144
	s_waitcnt lgkmcnt(10)
	v_mfma_f32_32x32x16_bf16 v[64:79], v[10:13], v[172:175], v[64:79]
	ds_read_b64_tr_b16 v[10:11], v250 offset:4096
	ds_read_b64_tr_b16 v[12:13], v250 offset:6144
	s_waitcnt lgkmcnt(10)
	v_mfma_f32_32x32x16_bf16 v[48:63], v[212:215], v[172:175], v[48:63]
	ds_read_b64_tr_b16 v[212:213], v251 offset:4096
	ds_read_b64_tr_b16 v[214:215], v251 offset:6144
	v_cvt_f32_u32_e32 v14, s67
	v_mul_f32_e32 v200, v196, v14
	v_max3_f32 v0, v128, s14, v129
	v_max3_f32 v0, v0, v130, v131
	v_max3_f32 v0, v0, v132, v133
	v_max3_f32 v0, v0, v134, v135
	s_waitcnt lgkmcnt(10)
	v_mfma_f32_32x32x16_bf16 v[32:47], v[240:243], v[172:175], v[32:47]
	ds_read_b64_tr_b16 v[240:241], v248 offset:8192
	ds_read_b64_tr_b16 v[242:243], v248 offset:10240
	v_max3_f32 v0, v0, v136, v137
	v_max3_f32 v0, v0, v138, v139
	v_max3_f32 v0, v0, v140, v141
	v_max3_f32 v0, v0, v142, v143
	s_waitcnt lgkmcnt(10)
	v_mfma_f32_32x32x16_bf16 v[16:31], v[244:247], v[172:175], v[16:31]
	ds_read_b64_tr_b16 v[244:245], v249 offset:8192
	ds_read_b64_tr_b16 v[246:247], v249 offset:10240
	v_max3_f32 v0, v0, v112, v113
	v_max3_f32 v0, v0, v114, v115
	v_max3_f32 v0, v0, v116, v117
	v_max3_f32 v0, v0, v118, v119
	v_max3_f32 v0, v0, v120, v121
	v_max3_f32 v0, v0, v122, v123
	v_max3_f32 v0, v0, v124, v125
	v_max3_f32 v0, v0, v126, v127
	ds_bpermute_b32 v15, v225, v0
	v_max_f32_e32 v0, v0, v0
	s_waitcnt lgkmcnt(11)
	v_mfma_f32_32x32x16_bf16 v[64:79], v[2:5], v[168:171], v[64:79]
	ds_read_b64_tr_b16 v[2:3], v250 offset:8192
	ds_read_b64_tr_b16 v[4:5], v250 offset:10240
	s_waitcnt lgkmcnt(11)
	v_mfma_f32_32x32x16_bf16 v[48:63], v[6:9], v[168:171], v[48:63]
	ds_read_b64_tr_b16 v[6:7], v251 offset:8192
	ds_read_b64_tr_b16 v[8:9], v251 offset:10240
	s_waitcnt lgkmcnt(4)
	v_max_f32_e32 v15, v15, v15
	v_max_f32_e32 v176, v0, v15
	v_add_f32_e32 v14, v200, v176
	v_max_f32_e32 v0, v14, v14
	v_max_f32_e32 v14, v201, v201
	v_max_f32_e32 v14, v14, v0
	v_mfma_f32_32x32x16_bf16 v[32:47], v[10:13], v[168:171], v[32:47]
	ds_read_b64_tr_b16 v[10:11], v248 offset:12288
	ds_read_b64_tr_b16 v[12:13], v248 offset:14336
	v_sub_f32_e32 v0, v201, v14
	v_exp_f32_e32 v0, v0
	v_sub_f32_e32 v15, v200, v14
	v_cmp_eq_f32_e32 vcc, 1.0, v0
	s_cmp_eq_u64 vcc, exec
	s_cselect_b64 s[42:43], 0, -1
	v_mov_b32_e32 v201, v14
	v_add_f32_e32 v128, v128, v15
	v_exp_f32_e32 v128, v128
	v_add_f32_e32 v129, v129, v15
	v_exp_f32_e32 v129, v129
	v_add_f32_e32 v238, 0, v128
	v_add_f32_e32 v130, v130, v15
	v_exp_f32_e32 v130, v130
	v_add_f32_e32 v238, v129, v238
	v_mfma_f32_32x32x16_bf16 v[16:31], v[212:215], v[168:171], v[16:31]
	ds_read_b64_tr_b16 v[212:213], v249 offset:12288
	ds_read_b64_tr_b16 v[214:215], v249 offset:14336
	v_add_f32_e32 v131, v131, v15
	v_exp_f32_e32 v131, v131
	v_add_f32_e32 v238, v130, v238
	v_add_f32_e32 v132, v132, v15
	v_exp_f32_e32 v132, v132
	v_add_f32_e32 v238, v131, v238
	v_add_f32_e32 v133, v133, v15
	v_exp_f32_e32 v133, v133
	v_add_f32_e32 v238, v132, v238
	v_add_f32_e32 v134, v134, v15
	v_exp_f32_e32 v134, v134
	v_add_f32_e32 v238, v133, v238
	v_mfma_f32_32x32x16_bf16 v[64:79], v[240:243], v[164:167], v[64:79]
	ds_read_b64_tr_b16 v[240:241], v250 offset:12288
	ds_read_b64_tr_b16 v[242:243], v250 offset:14336
	v_add_f32_e32 v135, v135, v15
	v_exp_f32_e32 v135, v135
	v_add_f32_e32 v238, v134, v238
	v_cvt_pk_bf16_f32 v172, v128, v129
	v_cvt_pk_bf16_f32 v173, v130, v131
	v_cvt_pk_bf16_f32 v174, v132, v133
	v_cvt_pk_bf16_f32 v175, v134, v135
	v_add_f32_e32 v136, v136, v15
	v_exp_f32_e32 v136, v136
	v_add_f32_e32 v238, v135, v238
	v_add_f32_e32 v137, v137, v15
	v_exp_f32_e32 v137, v137
	v_add_f32_e32 v238, v136, v238
	v_mfma_f32_32x32x16_bf16 v[48:63], v[244:247], v[164:167], v[48:63]
	ds_read_b64_tr_b16 v[244:245], v251 offset:12288
	ds_read_b64_tr_b16 v[246:247], v251 offset:14336
	v_add_f32_e32 v138, v138, v15
	v_exp_f32_e32 v138, v138
	v_add_f32_e32 v238, v137, v238
	v_add_f32_e32 v139, v139, v15
	v_exp_f32_e32 v139, v139
	v_add_f32_e32 v238, v138, v238
	v_add_f32_e32 v140, v140, v15
	v_exp_f32_e32 v140, v140
	v_add_f32_e32 v238, v139, v238
	v_add_f32_e32 v141, v141, v15
	v_exp_f32_e32 v141, v141
	v_add_f32_e32 v238, v140, v238
	s_waitcnt lgkmcnt(10)
	v_mfma_f32_32x32x16_bf16 v[32:47], v[2:5], v[164:167], v[32:47]
	v_add_f32_e32 v142, v142, v15
	v_exp_f32_e32 v142, v142
	v_add_f32_e32 v238, v141, v238
	v_add_f32_e32 v143, v143, v15
	v_exp_f32_e32 v143, v143
	v_add_f32_e32 v238, v142, v238
	v_cvt_pk_bf16_f32 v168, v136, v137
	v_cvt_pk_bf16_f32 v169, v138, v139
	v_cvt_pk_bf16_f32 v170, v140, v141
	v_cvt_pk_bf16_f32 v171, v142, v143
	v_add_f32_e32 v112, v112, v15
	v_exp_f32_e32 v112, v112
	v_add_f32_e32 v238, v143, v238
	v_add_f32_e32 v113, v113, v15
	v_exp_f32_e32 v113, v113
	v_add_f32_e32 v238, v112, v238
	s_waitcnt lgkmcnt(8)
	v_mfma_f32_32x32x16_bf16 v[16:31], v[6:9], v[164:167], v[16:31]
	v_add_f32_e32 v114, v114, v15
	v_exp_f32_e32 v114, v114
	v_add_f32_e32 v238, v113, v238
	v_add_f32_e32 v115, v115, v15
	v_exp_f32_e32 v115, v115
	v_add_f32_e32 v238, v114, v238
	v_add_f32_e32 v116, v116, v15
	v_exp_f32_e32 v116, v116
	v_add_f32_e32 v238, v115, v238
	v_add_f32_e32 v117, v117, v15
	v_exp_f32_e32 v117, v117
	v_add_f32_e32 v238, v116, v238
	s_waitcnt lgkmcnt(6)
	v_mfma_f32_32x32x16_bf16 v[64:79], v[10:13], v[160:163], v[64:79]
	v_add_f32_e32 v118, v118, v15
	v_exp_f32_e32 v118, v118
	v_add_f32_e32 v238, v117, v238
	v_add_f32_e32 v119, v119, v15
	v_exp_f32_e32 v119, v119
	v_add_f32_e32 v238, v118, v238
	v_cvt_pk_bf16_f32 v164, v112, v113
	v_cvt_pk_bf16_f32 v165, v114, v115
	v_cvt_pk_bf16_f32 v166, v116, v117
	v_cvt_pk_bf16_f32 v167, v118, v119
	v_add_f32_e32 v120, v120, v15
	v_exp_f32_e32 v120, v120
	v_add_f32_e32 v238, v119, v238
	s_waitcnt lgkmcnt(4)
	v_mfma_f32_32x32x16_bf16 v[48:63], v[212:215], v[160:163], v[48:63]
	v_add_f32_e32 v121, v121, v15
	v_exp_f32_e32 v121, v121
	v_add_f32_e32 v238, v120, v238
	v_add_f32_e32 v122, v122, v15
	v_exp_f32_e32 v122, v122
	v_add_f32_e32 v238, v121, v238
	s_waitcnt lgkmcnt(2)
	v_mfma_f32_32x32x16_bf16 v[32:47], v[240:243], v[160:163], v[32:47]
	v_add_f32_e32 v123, v123, v15
	v_exp_f32_e32 v123, v123
	v_add_f32_e32 v238, v122, v238
	v_add_f32_e32 v124, v124, v15
	v_exp_f32_e32 v124, v124
	v_add_f32_e32 v238, v123, v238
	s_waitcnt lgkmcnt(0)
	v_mfma_f32_32x32x16_bf16 v[16:31], v[244:247], v[160:163], v[16:31]
	v_add_f32_e32 v125, v125, v15
	v_exp_f32_e32 v125, v125
	v_add_f32_e32 v238, v124, v238
	v_add_f32_e32 v126, v126, v15
	v_exp_f32_e32 v126, v126
	v_add_f32_e32 v238, v125, v238
	v_add_f32_e32 v127, v127, v15
	v_exp_f32_e32 v127, v127
	v_add_f32_e32 v238, v126, v238
	v_cvt_pk_bf16_f32 v160, v120, v121
	v_cvt_pk_bf16_f32 v161, v122, v123
	v_cvt_pk_bf16_f32 v162, v124, v125
	v_cvt_pk_bf16_f32 v163, v126, v127
	v_add_f32_e32 v238, v127, v238
	v_fmac_f32_e32 v238, v232, v0
	s_mov_b32 s27, s30
	v_mov_b32_e32 v232, v238
	s_and_b64 vcc, exec, s[42:43]
	s_cbranch_vccz .Lfa_noresc
	s_nop 15
	v_pk_mul_f32 v[78:79], v[78:79], v[0:1] op_sel_hi:[1,0]
	v_pk_mul_f32 v[76:77], v[76:77], v[0:1] op_sel_hi:[1,0]
	v_pk_mul_f32 v[74:75], v[74:75], v[0:1] op_sel_hi:[1,0]
	v_pk_mul_f32 v[72:73], v[72:73], v[0:1] op_sel_hi:[1,0]
	v_pk_mul_f32 v[70:71], v[70:71], v[0:1] op_sel_hi:[1,0]
	v_pk_mul_f32 v[68:69], v[68:69], v[0:1] op_sel_hi:[1,0]
	v_pk_mul_f32 v[66:67], v[66:67], v[0:1] op_sel_hi:[1,0]
	v_pk_mul_f32 v[64:65], v[64:65], v[0:1] op_sel_hi:[1,0]
	v_pk_mul_f32 v[62:63], v[62:63], v[0:1] op_sel_hi:[1,0]
	v_pk_mul_f32 v[60:61], v[60:61], v[0:1] op_sel_hi:[1,0]
	v_pk_mul_f32 v[58:59], v[58:59], v[0:1] op_sel_hi:[1,0]
	v_pk_mul_f32 v[56:57], v[56:57], v[0:1] op_sel_hi:[1,0]
	v_pk_mul_f32 v[54:55], v[54:55], v[0:1] op_sel_hi:[1,0]
	v_pk_mul_f32 v[52:53], v[52:53], v[0:1] op_sel_hi:[1,0]
	v_pk_mul_f32 v[50:51], v[50:51], v[0:1] op_sel_hi:[1,0]
	v_pk_mul_f32 v[48:49], v[48:49], v[0:1] op_sel_hi:[1,0]
	v_pk_mul_f32 v[46:47], v[46:47], v[0:1] op_sel_hi:[1,0]
	v_pk_mul_f32 v[44:45], v[44:45], v[0:1] op_sel_hi:[1,0]
	v_pk_mul_f32 v[42:43], v[42:43], v[0:1] op_sel_hi:[1,0]
	v_pk_mul_f32 v[40:41], v[40:41], v[0:1] op_sel_hi:[1,0]
	v_pk_mul_f32 v[38:39], v[38:39], v[0:1] op_sel_hi:[1,0]
	v_pk_mul_f32 v[36:37], v[36:37], v[0:1] op_sel_hi:[1,0]
	v_pk_mul_f32 v[34:35], v[34:35], v[0:1] op_sel_hi:[1,0]
	v_pk_mul_f32 v[32:33], v[32:33], v[0:1] op_sel_hi:[1,0]
	v_pk_mul_f32 v[30:31], v[30:31], v[0:1] op_sel_hi:[1,0]
	v_pk_mul_f32 v[28:29], v[28:29], v[0:1] op_sel_hi:[1,0]
	v_pk_mul_f32 v[26:27], v[26:27], v[0:1] op_sel_hi:[1,0]
	v_pk_mul_f32 v[24:25], v[24:25], v[0:1] op_sel_hi:[1,0]
	v_pk_mul_f32 v[22:23], v[22:23], v[0:1] op_sel_hi:[1,0]
	v_pk_mul_f32 v[20:21], v[20:21], v[0:1] op_sel_hi:[1,0]
	v_pk_mul_f32 v[18:19], v[18:19], v[0:1] op_sel_hi:[1,0]
	v_pk_mul_f32 v[16:17], v[16:17], v[0:1] op_sel_hi:[1,0]
.Lfa_noresc:
	s_and_b64 vcc, exec, s[38:39]
	s_cbranch_vccz .LBB0_477
	s_branch .LBB0_480
.Lfa_slow:
	v_add_u32_e32 v0, s27, v227
	v_add_u32_e32 v14, s27, v228
	v_add_u32_e32 v15, s27, v229
	v_add_u32_e32 v116, s27, v230
	ds_read_b64_tr_b16 v[112:113], v0 offset:0
	ds_read_b64_tr_b16 v[114:115], v0 offset:2048
	ds_read_b64_tr_b16 v[10:11], v14 offset:0
	ds_read_b64_tr_b16 v[12:13], v14 offset:2048
	ds_read_b64_tr_b16 v[6:7], v15 offset:0
	ds_read_b64_tr_b16 v[8:9], v15 offset:2048
	ds_read_b64_tr_b16 v[2:3], v116 offset:0
	ds_read_b64_tr_b16 v[4:5], v116 offset:2048
	s_waitcnt lgkmcnt(0)
	s_mov_b64 s[96:97], 0
	v_mfma_f32_32x32x16_bf16 v[64:79], v[112:115], v[172:175], v[64:79]
	v_mfma_f32_32x32x16_bf16 v[48:63], v[10:13], v[172:175], v[48:63]
	v_mfma_f32_32x32x16_bf16 v[32:47], v[6:9], v[172:175], v[32:47]
	v_mfma_f32_32x32x16_bf16 v[16:31], v[2:5], v[172:175], v[16:31]
	ds_read_b64_tr_b16 v[112:113], v0 offset:4096
	ds_read_b64_tr_b16 v[114:115], v0 offset:6144
	ds_read_b64_tr_b16 v[10:11], v14 offset:4096
	ds_read_b64_tr_b16 v[12:13], v14 offset:6144
	ds_read_b64_tr_b16 v[6:7], v15 offset:4096
	ds_read_b64_tr_b16 v[8:9], v15 offset:6144
	ds_read_b64_tr_b16 v[2:3], v116 offset:4096
	ds_read_b64_tr_b16 v[4:5], v116 offset:6144
	s_waitcnt lgkmcnt(0)
	s_nop 0
	v_mfma_f32_32x32x16_bf16 v[64:79], v[112:115], v[168:171], v[64:79]
	v_mfma_f32_32x32x16_bf16 v[48:63], v[10:13], v[168:171], v[48:63]
	v_mfma_f32_32x32x16_bf16 v[32:47], v[6:9], v[168:171], v[32:47]
	v_mfma_f32_32x32x16_bf16 v[16:31], v[2:5], v[168:171], v[16:31]
	ds_read_b64_tr_b16 v[112:113], v0 offset:8192
	ds_read_b64_tr_b16 v[114:115], v0 offset:10240
	ds_read_b64_tr_b16 v[10:11], v14 offset:8192
	ds_read_b64_tr_b16 v[12:13], v14 offset:10240
	ds_read_b64_tr_b16 v[6:7], v15 offset:8192
	ds_read_b64_tr_b16 v[8:9], v15 offset:10240
	ds_read_b64_tr_b16 v[2:3], v116 offset:8192
	ds_read_b64_tr_b16 v[4:5], v116 offset:10240
	s_waitcnt lgkmcnt(0)
	s_nop 0
	v_mfma_f32_32x32x16_bf16 v[64:79], v[112:115], v[164:167], v[64:79]
	v_mfma_f32_32x32x16_bf16 v[48:63], v[10:13], v[164:167], v[48:63]
	v_mfma_f32_32x32x16_bf16 v[32:47], v[6:9], v[164:167], v[32:47]
	v_mfma_f32_32x32x16_bf16 v[16:31], v[2:5], v[164:167], v[16:31]
	ds_read_b64_tr_b16 v[112:113], v0 offset:12288
	ds_read_b64_tr_b16 v[114:115], v0 offset:14336
	ds_read_b64_tr_b16 v[10:11], v14 offset:12288
	ds_read_b64_tr_b16 v[12:13], v14 offset:14336
	ds_read_b64_tr_b16 v[6:7], v15 offset:12288
	ds_read_b64_tr_b16 v[8:9], v15 offset:14336
	ds_read_b64_tr_b16 v[2:3], v116 offset:12288
	ds_read_b64_tr_b16 v[4:5], v116 offset:14336
	s_waitcnt lgkmcnt(0)
	s_nop 0
	v_mfma_f32_32x32x16_bf16 v[64:79], v[112:115], v[160:163], v[64:79]
	v_mfma_f32_32x32x16_bf16 v[48:63], v[10:13], v[160:163], v[48:63]
	v_mfma_f32_32x32x16_bf16 v[32:47], v[6:9], v[160:163], v[32:47]
	v_mfma_f32_32x32x16_bf16 v[16:31], v[2:5], v[160:163], v[16:31]
